# E1->E2 grid barrier replaced by per-row-block completion counters (deferred signal, H stored write-through, E2 ticket holder polls)
# speedup vs baseline: 1.0380x; 1.0125x over previous
; __device__ __forceinline__ unsigned my_xcc_id() { return (unsigned)__builtin_amdgcn_s_getreg((3 << 11) | 20) & 7u; }
; template <class F>
; __device__ __forceinline__ void xcd_queue_run(unsigned* qwords, int nper, char* smem_aux, F fn) {
;   volatile int* slot = (volatile int*)smem_aux;
;   const unsigned x = my_xcc_id();
;   for (int dj = 0; dj < 8; dj++) {
;     const int j = (int)((x + dj) & 7u);
;     for (;;) {
; __device__ void phaseE1(const Params& p, char* smem) {
;   int* s_off = (int*)(smem + 2 * GEMM_SMEM);
;   int* s_rb = s_off + 72;
;   moe_prefix(p, s_off, s_rb);
;   xcd_queue_run(p.bar + QW_BASE + 1024, s_rb[NEXP], smem + 2 * GEMM_SMEM + 800, [&](int j, int q) {
;     const int rbg = q, jt = j;
;     int e = 0;
;     while (s_rb[e + 1] <= rbg) e++;
;     const int rb = rbg - s_rb[e];
;     const int cnt = p.cnt[e];
;     const int rows = min(128, cnt - rb * 128);
;     const int* lt = p.list_tok + e * CAP + rb * 128;
;     const int slot0 = s_off[e] + rb * 128;
;     const int j0 = jt * 64;
;     const u16* wg = p.WgT + (size_t)e * DEXP * DM;
;     const u16* wu = p.WuT + (size_t)e * DEXP * DM;
;     auto rowf = [&](int r) { int rr = r < rows ? r : 0; return (const void*)(p.X1B + (size_t)lt[rr] * DM); };
;     auto colf = [&](int c) { return (const void*)(((c & 32) ? wu : wg) + (size_t)(j0 + (c >> 6) * 32 + (c & 31)) * DM); };
.LBB0_1264:
	s_or_b64 exec, exec, s[0:1]
	s_mov_b64 s[0:1], src_shared_base
	s_add_u32 s0, s82, 0x4600
	s_addc_u32 s22, s83, 0
	s_add_i32 s2, 0, 0x10220
	v_mov_b32_e32 v0, s2
	s_waitcnt lgkmcnt(0)
	s_barrier
	ds_read_b32 v153, v0
	v_add_u32_e32 v150, 32, v160
	v_and_b32_e32 v0, 0x100, v128
	v_add_u32_e32 v151, 64, v160
	v_cmp_eq_u32_e64 s[6:7], 0, v0
	v_lshrrev_b32_e32 v0, 1, v150
	v_add_u32_e32 v152, 0x60, v160
	v_and_b32_e32 v156, 0x60, v0
	v_lshrrev_b32_e32 v0, 1, v151
	v_and_b32_e32 v157, 0x60, v0
	v_and_b32_e32 v0, 32, v152
	v_cmp_eq_u32_e64 s[8:9], 0, v0
	v_lshrrev_b32_e32 v0, 1, v152
	v_and_b32_e32 v158, 0x60, v0
	v_lshlrev_b32_e32 v0, 6, v128
	v_and_b32_e32 v1, 32, v133
	s_getreg_b32 s23, hwreg(HW_REG_XCC_ID, 0, 4)
	v_bfe_u32 v154, v128, 3, 5
	v_and_b32_e32 v155, 32, v132
	v_and_b32_e32 v0, 0x13c0, v0
	v_mov_b32_e32 v97, 0
	v_lshlrev_b32_e32 v96, 1, v1
	s_add_u32 s10, s56, 0x80
	s_mov_b32 s3, 0
	v_lshl_add_u64 v[98:99], s[58:59], 0, v[96:97]
	v_lshl_add_u64 v[100:101], s[56:57], 0, v[124:125]
	s_mov_b64 s[4:5], 0x80
	s_addc_u32 s11, s57, 0
	v_or_b32_e32 v159, v155, v154
	s_lshl_b32 s24, s23, 6
	v_or_b32_e32 v172, v156, v154
	v_or_b32_e32 v173, v157, v154
	v_or_b32_e32 v174, v158, v154
	v_lshlrev_b32_e32 v102, 1, v134
	v_mov_b32_e32 v103, v97
	s_add_i32 s25, 0, 0x10124
	v_lshlrev_b32_e32 v175, 1, v0
	s_mov_b32 s26, 0
	s_mov_b32 s32, -1
	s_mov_b32 s51, -1
	s_branch .LBB0_1266
.LBB0_1265:
	s_or_b64 exec, exec, s[14:15]
	s_waitcnt vmcnt(0)
	s_add_i32 s26, s26, 1
	s_add_i32 s24, s24, 64
	s_cmp_lg_u32 s26, 8
	s_cbranch_scc0 .LBB0_1290

; template <class F>
; __device__ __forceinline__ void xcd_queue_run(unsigned* qwords, int nper, char* smem_aux, F fn) {
;     ...
;   for (int dj = 0; dj < 8; dj++) {
;     const int j = (int)((x + dj) & 7u);
;     for (;;) {
;       __syncthreads();
;       if (threadIdx.x == 0) *slot = (int)__hip_atomic_fetch_add(qwords + 64 * j, 1u, __ATOMIC_RELAXED, __HIP_MEMORY_SCOPE_AGENT);
;       __syncthreads();
;       const int q = *slot;
.LBB0_1269:
	s_waitcnt lgkmcnt(0)
	s_barrier
	s_and_saveexec_b64 s[16:17], s[34:35]
	s_cbranch_execz .LBB0_1273
	s_cmp_lt_i32 s51, 0
	s_cbranch_scc1 .Le1_nosig
	s_lshr_b32 s49, s51, 5
	s_lshl_b32 s49, s49, 8
	s_and_b32 s50, s51, 31
	s_lshl_b32 s50, s50, 2
	s_add_u32 s49, s49, s50
	s_addk_i32 s49, 0x4604
	v_mov_b32_e32 v0, s49
	v_mov_b32_e32 v1, 1
	global_atomic_add v0, v1, s[82:83]
.Le1_nosig:
	s_mov_b32 s51, s32
	s_mov_b32 s32, -1
	s_mov_b64 s[20:21], exec
	v_mbcnt_lo_u32_b32 v0, s20, 0
	v_mbcnt_hi_u32_b32 v0, s21, v0
	v_cmp_eq_u32_e32 vcc, 0, v0
	s_and_saveexec_b64 s[18:19], vcc
	s_cbranch_execz .LBB0_1272
	s_bcnt1_i32_b64 s2, s[20:21]
	v_mov_b32_e32 v1, s2
	global_atomic_add v1, v97, v1, s[12:13] sc0

; template <class F>
; __device__ __forceinline__ void xcd_queue_run(unsigned* qwords, int nper, char* smem_aux, F fn) {
;     ...
;       __syncthreads();
;       if (threadIdx.x == 0) *slot = (int)__hip_atomic_fetch_add(qwords + 64 * j, 1u, __ATOMIC_RELAXED, __HIP_MEMORY_SCOPE_AGENT);
;       __syncthreads();
;       const int q = *slot;
;       if (q >= nper) break;
; __device__ void phaseE1(const Params& p, char* smem) {
;     ...
;     const int rbg = q, jt = j;
;     int e = 0;
;     while (s_rb[e + 1] <= rbg) e++;
;     const int rb = rbg - s_rb[e];
;     const int cnt = p.cnt[e];
;     const int rows = min(128, cnt - rb * 128);
;     const int* lt = p.list_tok + e * CAP + rb * 128;
;     const int slot0 = s_off[e] + rb * 128;
;     const int j0 = jt * 64;
;     const u16* wg = p.WgT + (size_t)e * DEXP * DM;
;     const u16* wu = p.WuT + (size_t)e * DEXP * DM;
;     auto rowf = [&](int r) { int rr = r < rows ? r : 0; return (const void*)(p.X1B + (size_t)lt[rr] * DM); };
;     auto colf = [&](int c) { return (const void*)(((c & 32) ? wu : wg) + (size_t)(j0 + (c >> 6) * 32 + (c & 31)) * DM); };
.LBB0_1273:
	s_or_b64 exec, exec, s[16:17]
	s_cmp_lg_u32 s33, -1
	s_cselect_b32 s2, s33, 0
	s_cselect_b32 s16, s1, 0
	v_mov_b32_e32 v0, s2
	v_mov_b32_e32 v1, s16
	s_waitcnt lgkmcnt(0)
	s_barrier
	flat_load_dword v0, v[0:1] sc0 sc1
	s_waitcnt vmcnt(0)
	s_mov_b64 s[18:19], -1
	s_waitcnt lgkmcnt(0)
	v_cmp_lt_i32_e32 vcc, v0, v153
	s_and_saveexec_b64 s[16:17], vcc
	s_cbranch_execz .LBB0_1268
	v_readfirstlane_b32 s32, v0
	v_lshrrev_b32_e32 v90, 4, v128
	v_xor_b32_e32 v90, v90, v128
	v_and_b32_e32 v90, 7, v90
	v_lshlrev_b32_e32 v92, 4, v90
	v_mov_b32_e32 v93, 0
	v_sub_u32_e32 v94, v92, v124
	v_lshrrev_b32_e32 v90, 6, v128
	v_ashrrev_i32_e32 v95, 31, v94
	v_readfirstlane_b32 s100, v90
	s_lshl_b32 s100, s100, 10
	s_mov_b64 s[18:19], 0
	v_mbcnt_lo_u32_b32 v1, -1, 0
	v_mbcnt_hi_u32_b32 v1, -1, v1
	v_lshl_add_u32 v1, v1, 2, s25
	ds_read_b32 v1, v1
	s_waitcnt lgkmcnt(0)
	v_cmp_le_i32_e32 vcc, v1, v0
	s_bcnt1_i32_b64 s2, vcc
	v_mov_b32_e32 v96, s2
	s_or_b64 exec, exec, s[18:19]
	v_lshl_add_u32 v6, v96, 2, 0
	v_add_u32_e32 v6, 0x10000, v6
	ds_read2_b32 v[6:7], v6 offset1:1
	v_lshl_add_u32 v10, v96, 2, 0
	v_add_u32_e32 v1, 0x10120, v10
	ds_read_b32 v1, v1
	v_lshlrev_b32_e32 v2, 15, v96
	v_mov_b32_e32 v3, v97
	v_lshl_add_u64 v[2:3], v[2:3], 2, s[68:69]
	v_lshlrev_b64 v[4:5], 20, v[96:97]
	s_waitcnt lgkmcnt(0)
	v_sub_u32_e32 v6, v7, v6
	v_sub_u32_e32 v0, v0, v1
	v_lshlrev_b32_e32 v122, 7, v0
	v_ashrrev_i32_e32 v123, 31, v122
	v_lshl_add_u64 v[0:1], v[122:123], 2, v[2:3]
	v_mov_b32_e32 v56, 0
	s_mov_b32 s2, 0
	s_mov_b32 s27, 0
	v_mov_b32_e32 v57, v56
	v_mov_b32_e32 v58, v56
	v_mov_b32_e32 v59, v56
	v_mov_b32_e32 v48, v56
	v_mov_b32_e32 v49, v56
	v_mov_b32_e32 v50, v56
	v_mov_b32_e32 v51, v56
	v_mov_b32_e32 v60, v56
	v_mov_b32_e32 v61, v56
	v_mov_b32_e32 v62, v56
	v_mov_b32_e32 v63, v56
	v_mov_b32_e32 v52, v56
	v_mov_b32_e32 v53, v56
	v_mov_b32_e32 v54, v56
	v_mov_b32_e32 v55, v56
	v_mov_b32_e32 v40, v56
	v_mov_b32_e32 v41, v56
	v_mov_b32_e32 v42, v56
	v_mov_b32_e32 v43, v56
	v_mov_b32_e32 v32, v56
	v_mov_b32_e32 v33, v56
	v_mov_b32_e32 v34, v56
	v_mov_b32_e32 v35, v56
	v_mov_b32_e32 v44, v56
	v_mov_b32_e32 v45, v56
	v_mov_b32_e32 v46, v56
	v_mov_b32_e32 v47, v56
	v_mov_b32_e32 v36, v56
	v_mov_b32_e32 v37, v56
	v_mov_b32_e32 v38, v56
	v_mov_b32_e32 v39, v56
	v_mov_b32_e32 v24, v56
	v_mov_b32_e32 v25, v56
	v_mov_b32_e32 v26, v56
	v_mov_b32_e32 v27, v56
	v_mov_b32_e32 v16, v56
	v_mov_b32_e32 v17, v56
	v_mov_b32_e32 v18, v56
	v_mov_b32_e32 v19, v56
	v_mov_b32_e32 v28, v56
	v_mov_b32_e32 v29, v56
	v_mov_b32_e32 v30, v56
	v_mov_b32_e32 v31, v56
	v_mov_b32_e32 v20, v56
	v_mov_b32_e32 v21, v56
	v_mov_b32_e32 v22, v56
	v_mov_b32_e32 v23, v56
	s_waitcnt vmcnt(0)
	v_sub_u32_e32 v2, v6, v122
	v_min_i32_e32 v123, 0x80, v2
	v_cmp_lt_i32_e32 vcc, v160, v123
	v_readfirstlane_b32 s98, v123
	s_lshr_b32 s99, s100, 11
	s_cmp_le_u32 s98, 64
	s_cselect_b32 s98, 1, 0
	s_and_b32 s99, s99, s98
	s_nop 1
	v_cndmask_b32_e32 v2, 0, v160, vcc
	v_cmp_lt_i32_e32 vcc, v150, v123
	v_lshlrev_b32_e32 v96, 2, v2
	v_lshl_add_u64 v[2:3], v[0:1], 0, v[96:97]
	v_cndmask_b32_e32 v6, 0, v150, vcc
	v_cmp_lt_i32_e32 vcc, v151, v123
	v_lshlrev_b32_e32 v96, 2, v6
	v_lshl_add_u64 v[6:7], v[0:1], 0, v[96:97]
	v_cndmask_b32_e32 v8, 0, v151, vcc
	v_cmp_lt_i32_e32 vcc, v152, v123
	v_lshlrev_b32_e32 v96, 2, v8
	v_lshl_add_u64 v[8:9], v[0:1], 0, v[96:97]
	v_cndmask_b32_e32 v11, 0, v152, vcc
	v_lshlrev_b32_e32 v96, 2, v11
	global_load_dword v2, v[2:3], off
	v_lshl_add_u64 v[0:1], v[0:1], 0, v[96:97]
	global_load_dword v6, v[6:7], off
	v_add_u32_e32 v96, 0x10000, v10
	global_load_dword v8, v[8:9], off
	v_lshl_add_u64 v[10:11], s[74:75], 0, v[4:5]
	global_load_dword v0, v[0:1], off
	v_lshl_add_u64 v[4:5], s[76:77], 0, v[4:5]
	v_cndmask_b32_e64 v133, v5, v11, s[6:7]
	v_cndmask_b32_e64 v132, v4, v10, s[6:7]
	v_cndmask_b32_e64 v135, v11, v5, s[6:7]
	v_cndmask_b32_e64 v134, v10, v4, s[6:7]
	v_cndmask_b32_e64 v137, v5, v11, s[8:9]
	v_cndmask_b32_e64 v136, v4, v10, s[8:9]
	v_lshl_add_u64 v[4:5], v[132:133], 0, v[112:113]
	v_lshl_add_u64 v[10:11], v[134:135], 0, v[114:115]
	v_lshl_add_u64 v[12:13], v[132:133], 0, v[116:117]
	v_lshl_add_u64 v[14:15], v[136:137], 0, v[118:119]
	v_lshl_add_u64 v[4:5], v[4:5], 0, v[92:93]
	v_lshl_add_u64 v[10:11], v[10:11], 0, v[92:93]
	v_lshl_add_u64 v[12:13], v[12:13], 0, v[92:93]
	v_lshl_add_u64 v[14:15], v[14:15], 0, v[92:93]
	s_add_u32 m0, s100, 0x4000
	s_nop 0
	global_load_lds_dwordx4 v[4:5], off
	s_add_u32 m0, s100, 0x5000
	s_nop 0
	global_load_lds_dwordx4 v[10:11], off
	s_add_u32 m0, s100, 0x6000
	s_nop 0
	global_load_lds_dwordx4 v[12:13], off
	s_add_u32 m0, s100, 0x7000
	s_nop 0
	global_load_lds_dwordx4 v[14:15], off
	v_lshl_add_u64 v[138:139], v[132:133], 0, s[4:5]
	v_lshl_add_u64 v[134:135], v[134:135], 0, v[106:107]
	v_lshl_add_u64 v[176:177], v[136:137], 0, v[110:111]
	v_mov_b32_e32 v10, v56
	v_mov_b32_e32 v11, v56
	v_mov_b32_e32 v12, v56
	v_mov_b32_e32 v13, v56
	v_mov_b32_e32 v14, v56
	v_mov_b32_e32 v15, v56
	v_lshl_add_u64 v[132:133], v[138:139], 0, v[104:105]
	v_lshl_add_u64 v[134:135], v[134:135], 0, s[4:5]
	v_lshl_add_u64 v[136:137], v[138:139], 0, v[108:109]
	v_lshl_add_u64 v[138:139], v[176:177], 0, s[4:5]
	s_waitcnt vmcnt(7)
	v_ashrrev_i32_e32 v3, 31, v2
	v_lshlrev_b64 v[140:141], 11, v[2:3]
	s_waitcnt vmcnt(6)
	v_ashrrev_i32_e32 v7, 31, v6
	v_lshl_add_u64 v[2:3], v[100:101], 0, v[140:141]
	s_waitcnt vmcnt(5)
	v_ashrrev_i32_e32 v9, 31, v8
	v_lshlrev_b64 v[144:145], 11, v[8:9]
	s_waitcnt vmcnt(4)
	v_ashrrev_i32_e32 v1, 31, v0
	v_lshlrev_b64 v[142:143], 11, v[6:7]
	v_lshl_add_u64 v[6:7], v[100:101], 0, v[144:145]
	v_lshlrev_b64 v[146:147], 11, v[0:1]
	v_lshl_add_u64 v[4:5], v[100:101], 0, v[142:143]
	s_add_u32 m0, s100, 0x0
	v_lshl_add_u64 v[90:91], v[2:3], 0, v[94:95]
	global_load_lds_dwordx4 v[90:91], off
	s_add_u32 m0, s100, 0x1000
	v_lshl_add_u64 v[90:91], v[4:5], 0, v[94:95]
	global_load_lds_dwordx4 v[90:91], off
	v_lshl_add_u64 v[0:1], v[100:101], 0, v[146:147]
	s_add_u32 m0, s100, 0x2000
	v_lshl_add_u64 v[90:91], v[6:7], 0, v[94:95]
	global_load_lds_dwordx4 v[90:91], off
	s_add_u32 m0, s100, 0x3000
	v_lshl_add_u64 v[90:91], v[0:1], 0, v[94:95]
	global_load_lds_dwordx4 v[90:91], off
	ds_read_b32 v96, v96
	v_mov_b32_e32 v8, v56
	v_mov_b32_e32 v9, v56
	v_mov_b32_e32 v0, v56
	v_mov_b32_e32 v1, v56
	v_mov_b32_e32 v2, v56
	v_mov_b32_e32 v3, v56
	v_mov_b32_e32 v4, v56
	v_mov_b32_e32 v5, v56
	v_mov_b32_e32 v6, v56
	v_lshl_add_u64 v[140:141], s[10:11], 0, v[140:141]
	v_lshl_add_u64 v[142:143], s[10:11], 0, v[142:143]
	v_lshl_add_u64 v[144:145], s[10:11], 0, v[144:145]
	v_lshl_add_u64 v[146:147], s[10:11], 0, v[146:147]
	v_mov_b32_e32 v7, v56
	s_waitcnt vmcnt(0)
	s_waitcnt lgkmcnt(0)
	s_barrier
	s_branch .LBB0_1278

; __device__ __forceinline__ float siluf(float x) { return x / (1.f + __expf(-x)); }
; __device__ void phaseE1(const Params& p, char* smem) {
;     ...
;     auto epi = [&](f32x4 (&acc)[4][4], int mb, int nb) {
;       const int wn = nb >> 6, kg4 = nb & 63;
; #pragma unroll
;       for (int mi = 0; mi < 4; mi++) {
;         const int r = mb + mi * 16;
;         if (r < rows) {
; #pragma unroll
;           for (int ni = 0; ni < 2; ni++) {
;             f32x4 gv = acc[mi][ni], uv = acc[mi][ni + 2];
;             uint2 o;
;             o.x = pack2(siluf(gv[0]) * uv[0], siluf(gv[1]) * uv[1]);
;             o.y = pack2(siluf(gv[2]) * uv[2], siluf(gv[3]) * uv[3]);
;             *(uint2*)&p.H[(size_t)(slot0 + r) * DEXP + j0 + wn * 32 + ni * 16 + kg4] = o;
;           }
;         }
;       }
;     };
.LBB0_1285:
	v_mul_f32_e32 v32, 0xbfb8aa3b, v24
	v_mul_f32_e32 v33, 0xbfb8aa3b, v25
	v_exp_f32_e32 v32, v32
	v_exp_f32_e32 v33, v33
	s_nop 0
	v_pk_add_f32 v[32:33], v[32:33], 1.0 op_sel_hi:[1,0]
	s_nop 0
	v_div_scale_f32 v34, s[20:21], v33, v33, v25
	v_rcp_f32_e32 v35, v34
	v_div_scale_f32 v36, vcc, v25, v33, v25
	v_fma_f32 v37, -v34, v35, 1.0
	v_fmac_f32_e32 v35, v37, v35
	v_mul_f32_e32 v37, v36, v35
	v_fma_f32 v38, -v34, v37, v36
	v_fmac_f32_e32 v37, v38, v35
	v_fma_f32 v34, -v34, v37, v36
	v_div_scale_f32 v36, s[20:21], v32, v32, v24
	v_rcp_f32_e32 v38, v36
	v_div_fmas_f32 v34, v34, v35, v37
	v_div_fixup_f32 v25, v34, v33, v25
	v_mul_f32_e32 v35, 0xbfb8aa3b, v27
	v_fma_f32 v33, -v36, v38, 1.0
	v_fmac_f32_e32 v38, v33, v38
	v_div_scale_f32 v33, vcc, v24, v32, v24
	v_mul_f32_e32 v37, v33, v38
	v_fma_f32 v34, -v36, v37, v33
	v_fmac_f32_e32 v37, v34, v38
	v_mul_f32_e32 v34, 0xbfb8aa3b, v26
	v_exp_f32_e32 v34, v34
	v_exp_f32_e32 v35, v35
	v_fma_f32 v33, -v36, v37, v33
	v_div_fmas_f32 v33, v33, v38, v37
	v_div_fixup_f32 v24, v33, v32, v24
	v_pk_add_f32 v[34:35], v[34:35], 1.0 op_sel_hi:[1,0]
	v_pk_mul_f32 v[24:25], v[28:29], v[24:25]
	v_div_scale_f32 v36, s[20:21], v35, v35, v27
	v_rcp_f32_e32 v37, v36
	v_cvt_pk_bf16_f32 v24, v24, v25
	v_fma_f32 v25, -v36, v37, 1.0
	v_fmac_f32_e32 v37, v25, v37
	v_div_scale_f32 v25, vcc, v27, v35, v27
	v_mul_f32_e32 v28, v25, v37
	v_fma_f32 v29, -v36, v28, v25
	v_fmac_f32_e32 v28, v29, v37
	v_div_scale_f32 v29, s[20:21], v34, v34, v26
	v_rcp_f32_e32 v32, v29
	v_fma_f32 v25, -v36, v28, v25
	v_div_fmas_f32 v25, v25, v37, v28
	v_div_fixup_f32 v27, v25, v35, v27
	v_fma_f32 v25, -v29, v32, 1.0
	v_fmac_f32_e32 v32, v25, v32
	v_div_scale_f32 v25, vcc, v26, v34, v26
	v_mul_f32_e32 v28, v25, v32
	v_fma_f32 v33, -v29, v28, v25
	v_fmac_f32_e32 v28, v33, v32
	v_fma_f32 v25, -v29, v28, v25
	v_div_fmas_f32 v25, v25, v32, v28
	v_div_fixup_f32 v26, v25, v34, v26
	v_mul_f32_e32 v25, 0xbfb8aa3b, v16
	v_exp_f32_e32 v28, v25
	v_mul_f32_e32 v25, 0xbfb8aa3b, v17
	v_exp_f32_e32 v29, v25
	v_pk_mul_f32 v[26:27], v[30:31], v[26:27]
	v_pk_add_f32 v[28:29], v[28:29], 1.0 op_sel_hi:[1,0]
	s_nop 0
	v_div_scale_f32 v30, s[20:21], v29, v29, v17
	v_cvt_pk_bf16_f32 v25, v26, v27
	v_add_u32_e32 v26, v64, v167
	v_rcp_f32_e32 v31, v30
	v_ashrrev_i32_e32 v27, 31, v26
	v_lshlrev_b64 v[26:27], 10, v[26:27]
	v_lshl_add_u64 v[26:27], v[120:121], 0, v[26:27]
	global_store_dwordx2 v[26:27], v[24:25], off sc0 sc1
	v_fma_f32 v24, -v30, v31, 1.0
	v_fmac_f32_e32 v31, v24, v31
	v_div_scale_f32 v24, vcc, v17, v29, v17
	v_mul_f32_e32 v25, v24, v31
	v_fma_f32 v32, -v30, v25, v24
	v_fmac_f32_e32 v25, v32, v31
	v_fma_f32 v24, -v30, v25, v24
	v_div_scale_f32 v30, s[20:21], v28, v28, v16
	v_rcp_f32_e32 v32, v30
	v_div_fmas_f32 v24, v24, v31, v25
	v_div_fixup_f32 v17, v24, v29, v17
	v_div_scale_f32 v29, vcc, v16, v28, v16
	v_fma_f32 v24, -v30, v32, 1.0
	v_fmac_f32_e32 v32, v24, v32
	v_mul_f32_e32 v31, v29, v32
	v_fma_f32 v24, -v30, v31, v29
	v_fmac_f32_e32 v31, v24, v32
	v_mul_f32_e32 v24, 0xbfb8aa3b, v18
	v_mul_f32_e32 v25, 0xbfb8aa3b, v19
	v_exp_f32_e32 v24, v24
	v_exp_f32_e32 v25, v25
	v_fma_f32 v29, -v30, v31, v29
	v_div_fmas_f32 v29, v29, v32, v31
	v_div_fixup_f32 v16, v29, v28, v16
	v_pk_add_f32 v[24:25], v[24:25], 1.0 op_sel_hi:[1,0]
	v_pk_mul_f32 v[16:17], v[20:21], v[16:17]
	v_div_scale_f32 v30, s[20:21], v25, v25, v19
	v_rcp_f32_e32 v31, v30
	v_cvt_pk_bf16_f32 v16, v16, v17
	v_fma_f32 v17, -v30, v31, 1.0
	v_fmac_f32_e32 v31, v17, v31
	v_div_scale_f32 v17, vcc, v19, v25, v19
	v_mul_f32_e32 v20, v17, v31
	v_fma_f32 v21, -v30, v20, v17
	v_fmac_f32_e32 v20, v21, v31
	v_div_scale_f32 v21, s[20:21], v24, v24, v18
	v_rcp_f32_e32 v28, v21
	v_fma_f32 v17, -v30, v20, v17
	v_div_fmas_f32 v17, v17, v31, v20
	v_div_fixup_f32 v19, v17, v25, v19
	v_fma_f32 v17, -v21, v28, 1.0
	v_fmac_f32_e32 v28, v17, v28
	v_div_scale_f32 v17, vcc, v18, v24, v18
	v_mul_f32_e32 v20, v17, v28
	v_fma_f32 v25, -v21, v20, v17
	v_fmac_f32_e32 v20, v25, v28
	v_fma_f32 v17, -v21, v20, v17
	v_div_fmas_f32 v17, v17, v28, v20
	v_div_fixup_f32 v18, v17, v24, v18
	v_pk_mul_f32 v[18:19], v[22:23], v[18:19]
	s_nop 0
	v_cvt_pk_bf16_f32 v17, v18, v19
	global_store_dwordx2 v[26:27], v[16:17], off offset:32 sc0 sc1
.LBB0_1286:
	s_or_b64 exec, exec, s[18:19]
	v_cmp_lt_i32_e32 vcc, v168, v123
	s_and_saveexec_b64 s[18:19], vcc
	s_xor_b64 s[18:19], exec, s[18:19]
	s_cbranch_execz .LBB0_1267
; __device__ __forceinline__ float siluf(float x) { return x / (1.f + __expf(-x)); }
; __device__ void phaseE1(const Params& p, char* smem) {
;     ...
;     auto epi = [&](f32x4 (&acc)[4][4], int mb, int nb) {
;       const int wn = nb >> 6, kg4 = nb & 63;
; #pragma unroll
;       for (int mi = 0; mi < 4; mi++) {
;         const int r = mb + mi * 16;
;         if (r < rows) {
; #pragma unroll
;           for (int ni = 0; ni < 2; ni++) {
;             f32x4 gv = acc[mi][ni], uv = acc[mi][ni + 2];
;             uint2 o;
;             o.x = pack2(siluf(gv[0]) * uv[0], siluf(gv[1]) * uv[1]);
;             o.y = pack2(siluf(gv[2]) * uv[2], siluf(gv[3]) * uv[3]);
;             *(uint2*)&p.H[(size_t)(slot0 + r) * DEXP + j0 + wn * 32 + ni * 16 + kg4] = o;
;           }
;         }
;       }
;     };
	v_mul_f32_e32 v16, 0xbfb8aa3b, v8
	v_mul_f32_e32 v17, 0xbfb8aa3b, v9
	v_exp_f32_e32 v16, v16
	v_exp_f32_e32 v17, v17
	s_nop 0
	v_pk_add_f32 v[16:17], v[16:17], 1.0 op_sel_hi:[1,0]
	s_nop 0
	v_div_scale_f32 v18, s[20:21], v17, v17, v9
	v_rcp_f32_e32 v19, v18
	v_div_scale_f32 v20, vcc, v9, v17, v9
	v_fma_f32 v21, -v18, v19, 1.0
	v_fmac_f32_e32 v19, v21, v19
	v_mul_f32_e32 v21, v20, v19
	v_fma_f32 v22, -v18, v21, v20
	v_fmac_f32_e32 v21, v22, v19
	v_fma_f32 v18, -v18, v21, v20
	v_div_scale_f32 v20, s[20:21], v16, v16, v8
	v_rcp_f32_e32 v22, v20
	v_div_fmas_f32 v18, v18, v19, v21
	v_div_fixup_f32 v9, v18, v17, v9
	v_mul_f32_e32 v19, 0xbfb8aa3b, v11
	v_fma_f32 v17, -v20, v22, 1.0
	v_fmac_f32_e32 v22, v17, v22
	v_div_scale_f32 v17, vcc, v8, v16, v8
	v_mul_f32_e32 v21, v17, v22
	v_fma_f32 v18, -v20, v21, v17
	v_fmac_f32_e32 v21, v18, v22
	v_mul_f32_e32 v18, 0xbfb8aa3b, v10
	v_exp_f32_e32 v18, v18
	v_exp_f32_e32 v19, v19
	v_fma_f32 v17, -v20, v21, v17
	v_div_fmas_f32 v17, v17, v22, v21
	v_div_fixup_f32 v8, v17, v16, v8
	v_pk_add_f32 v[18:19], v[18:19], 1.0 op_sel_hi:[1,0]
	v_pk_mul_f32 v[8:9], v[12:13], v[8:9]
	v_div_scale_f32 v20, s[20:21], v19, v19, v11
	v_rcp_f32_e32 v21, v20
	v_cvt_pk_bf16_f32 v8, v8, v9
	v_fma_f32 v9, -v20, v21, 1.0
	v_fmac_f32_e32 v21, v9, v21
	v_div_scale_f32 v9, vcc, v11, v19, v11
	v_mul_f32_e32 v12, v9, v21
	v_fma_f32 v13, -v20, v12, v9
	v_fmac_f32_e32 v12, v13, v21
	v_div_scale_f32 v13, s[20:21], v18, v18, v10
	v_rcp_f32_e32 v16, v13
	v_fma_f32 v9, -v20, v12, v9
	v_div_fmas_f32 v9, v9, v21, v12
	v_div_fixup_f32 v11, v9, v19, v11
	v_fma_f32 v9, -v13, v16, 1.0
	v_fmac_f32_e32 v16, v9, v16
	v_div_scale_f32 v9, vcc, v10, v18, v10
	v_mul_f32_e32 v12, v9, v16
	v_fma_f32 v17, -v13, v12, v9
	v_fmac_f32_e32 v12, v17, v16
	v_fma_f32 v9, -v13, v12, v9
	v_div_fmas_f32 v9, v9, v16, v12
	v_div_fixup_f32 v10, v9, v18, v10
	v_mul_f32_e32 v9, 0xbfb8aa3b, v0
	v_exp_f32_e32 v12, v9
	v_mul_f32_e32 v9, 0xbfb8aa3b, v1
	v_exp_f32_e32 v13, v9
	v_pk_mul_f32 v[10:11], v[14:15], v[10:11]
	v_pk_add_f32 v[12:13], v[12:13], 1.0 op_sel_hi:[1,0]
	s_nop 0
	v_div_scale_f32 v14, s[20:21], v13, v13, v1
	v_cvt_pk_bf16_f32 v9, v10, v11
	v_add_u32_e32 v10, v64, v168
	v_rcp_f32_e32 v15, v14
	v_ashrrev_i32_e32 v11, 31, v10
	v_lshlrev_b64 v[10:11], 10, v[10:11]
	v_lshl_add_u64 v[10:11], v[120:121], 0, v[10:11]
	global_store_dwordx2 v[10:11], v[8:9], off sc0 sc1
	v_fma_f32 v8, -v14, v15, 1.0
	v_fmac_f32_e32 v15, v8, v15
	v_div_scale_f32 v8, vcc, v1, v13, v1
	v_mul_f32_e32 v9, v8, v15
	v_fma_f32 v16, -v14, v9, v8
	v_fmac_f32_e32 v9, v16, v15
	v_fma_f32 v8, -v14, v9, v8
	v_div_scale_f32 v14, s[20:21], v12, v12, v0
	v_rcp_f32_e32 v16, v14
	v_div_fmas_f32 v8, v8, v15, v9
	v_div_fixup_f32 v1, v8, v13, v1
	v_div_scale_f32 v13, vcc, v0, v12, v0
	v_fma_f32 v8, -v14, v16, 1.0
	v_fmac_f32_e32 v16, v8, v16
	v_mul_f32_e32 v15, v13, v16
	v_fma_f32 v8, -v14, v15, v13
	v_fmac_f32_e32 v15, v8, v16
	v_mul_f32_e32 v8, 0xbfb8aa3b, v2
	v_mul_f32_e32 v9, 0xbfb8aa3b, v3
	v_exp_f32_e32 v8, v8
	v_exp_f32_e32 v9, v9
	v_fma_f32 v13, -v14, v15, v13
	v_div_fmas_f32 v13, v13, v16, v15
	v_div_fixup_f32 v0, v13, v12, v0
	v_pk_add_f32 v[8:9], v[8:9], 1.0 op_sel_hi:[1,0]
	v_pk_mul_f32 v[0:1], v[4:5], v[0:1]
	v_div_scale_f32 v14, s[20:21], v9, v9, v3
	v_rcp_f32_e32 v15, v14
	v_cvt_pk_bf16_f32 v0, v0, v1
	v_fma_f32 v1, -v14, v15, 1.0
	v_fmac_f32_e32 v15, v1, v15
	v_div_scale_f32 v1, vcc, v3, v9, v3
	v_mul_f32_e32 v4, v1, v15
	v_fma_f32 v5, -v14, v4, v1
	v_fmac_f32_e32 v4, v5, v15
	v_div_scale_f32 v5, s[20:21], v8, v8, v2
	v_rcp_f32_e32 v12, v5
	v_fma_f32 v1, -v14, v4, v1
	v_div_fmas_f32 v1, v1, v15, v4
	v_div_fixup_f32 v3, v1, v9, v3
	v_fma_f32 v1, -v5, v12, 1.0
	v_fmac_f32_e32 v12, v1, v12
	v_div_scale_f32 v1, vcc, v2, v8, v2
	v_mul_f32_e32 v4, v1, v12
	v_fma_f32 v9, -v5, v4, v1
	v_fmac_f32_e32 v4, v9, v12
	v_fma_f32 v1, -v5, v4, v1
	v_div_fmas_f32 v1, v1, v12, v4
	v_div_fixup_f32 v2, v1, v8, v2
	v_pk_mul_f32 v[2:3], v[6:7], v[2:3]
	s_nop 0
	v_cvt_pk_bf16_f32 v1, v2, v3
	global_store_dwordx2 v[10:11], v[0:1], off offset:32 sc0 sc1
	s_branch .LBB0_1267
.LBB0_1288:
	v_mul_f32_e32 v65, 0xbfb8aa3b, v56
	v_exp_f32_e32 v66, v65
	v_mul_f32_e32 v65, 0xbfb8aa3b, v57
	v_exp_f32_e32 v67, v65
	s_nop 0
	v_pk_add_f32 v[66:67], v[66:67], 1.0 op_sel_hi:[1,0]
	s_nop 0
	v_div_scale_f32 v65, s[20:21], v67, v67, v57
	s_waitcnt vmcnt(2)
	v_rcp_f32_e32 v68, v65
	v_div_scale_f32 v69, vcc, v57, v67, v57
	v_fma_f32 v70, -v65, v68, 1.0
	v_fmac_f32_e32 v68, v70, v68
	v_mul_f32_e32 v70, v69, v68
	v_fma_f32 v71, -v65, v70, v69
	v_fmac_f32_e32 v70, v71, v68
	v_div_scale_f32 v71, s[20:21], v66, v66, v56
	s_waitcnt vmcnt(1)
; __device__ __forceinline__ float siluf(float x) { return x / (1.f + __expf(-x)); }
; __device__ void phaseE1(const Params& p, char* smem) {
;     ...
;     auto epi = [&](f32x4 (&acc)[4][4], int mb, int nb) {
;       const int wn = nb >> 6, kg4 = nb & 63;
; #pragma unroll
;       for (int mi = 0; mi < 4; mi++) {
;         const int r = mb + mi * 16;
;         if (r < rows) {
; #pragma unroll
;           for (int ni = 0; ni < 2; ni++) {
;             f32x4 gv = acc[mi][ni], uv = acc[mi][ni + 2];
;             uint2 o;
;             o.x = pack2(siluf(gv[0]) * uv[0], siluf(gv[1]) * uv[1]);
;             o.y = pack2(siluf(gv[2]) * uv[2], siluf(gv[3]) * uv[3]);
;             *(uint2*)&p.H[(size_t)(slot0 + r) * DEXP + j0 + wn * 32 + ni * 16 + kg4] = o;
;           }
;         }
;       }
;     };
	v_rcp_f32_e32 v72, v71
	v_fma_f32 v65, -v65, v70, v69
	v_div_fmas_f32 v65, v65, v68, v70
	v_div_fixup_f32 v57, v65, v67, v57
	v_fma_f32 v65, -v71, v72, 1.0
	v_fmac_f32_e32 v72, v65, v72
	v_div_scale_f32 v65, vcc, v56, v66, v56
	v_mul_f32_e32 v67, v65, v72
	v_fma_f32 v68, -v71, v67, v65
	v_fmac_f32_e32 v67, v68, v72
	v_mul_f32_e32 v68, 0xbfb8aa3b, v58
	v_mul_f32_e32 v69, 0xbfb8aa3b, v59
	v_exp_f32_e32 v68, v68
	v_exp_f32_e32 v69, v69
	v_fma_f32 v65, -v71, v67, v65
	v_div_fmas_f32 v65, v65, v72, v67
	v_div_fixup_f32 v56, v65, v66, v56
	v_pk_add_f32 v[68:69], v[68:69], 1.0 op_sel_hi:[1,0]
	v_pk_mul_f32 v[56:57], v[60:61], v[56:57]
	v_div_scale_f32 v67, s[20:21], v69, v69, v59
	v_rcp_f32_e32 v70, v67
	v_cvt_pk_bf16_f32 v56, v56, v57
	v_fma_f32 v57, -v67, v70, 1.0
	v_fmac_f32_e32 v70, v57, v70
	v_div_scale_f32 v57, vcc, v59, v69, v59
	v_mul_f32_e32 v60, v57, v70
	v_fma_f32 v61, -v67, v60, v57
	v_fmac_f32_e32 v60, v61, v70
	v_div_scale_f32 v61, s[20:21], v68, v68, v58
	v_rcp_f32_e32 v65, v61
	v_fma_f32 v57, -v67, v60, v57
	v_div_fmas_f32 v57, v57, v70, v60
	v_div_fixup_f32 v59, v57, v69, v59
	v_fma_f32 v57, -v61, v65, 1.0
	v_fmac_f32_e32 v65, v57, v65
	v_div_scale_f32 v57, vcc, v58, v68, v58
	v_mul_f32_e32 v60, v57, v65
	v_fma_f32 v66, -v61, v60, v57
	v_fmac_f32_e32 v60, v66, v65
	v_fma_f32 v57, -v61, v60, v57
	v_div_fmas_f32 v57, v57, v65, v60
	v_div_fixup_f32 v58, v57, v68, v58
	v_mul_f32_e32 v57, 0xbfb8aa3b, v48
	v_exp_f32_e32 v60, v57
	v_mul_f32_e32 v57, 0xbfb8aa3b, v49
	v_exp_f32_e32 v61, v57
	v_pk_mul_f32 v[58:59], v[62:63], v[58:59]
	v_pk_add_f32 v[60:61], v[60:61], 1.0 op_sel_hi:[1,0]
	s_nop 0
	v_div_scale_f32 v62, s[20:21], v61, v61, v49
	v_cvt_pk_bf16_f32 v57, v58, v59
	v_add_u32_e32 v58, v64, v126
	v_rcp_f32_e32 v63, v62
	v_ashrrev_i32_e32 v59, 31, v58
	v_lshlrev_b64 v[58:59], 10, v[58:59]
	v_lshl_add_u64 v[58:59], v[120:121], 0, v[58:59]
	global_store_dwordx2 v[58:59], v[56:57], off sc0 sc1
	v_fma_f32 v56, -v62, v63, 1.0
	v_fmac_f32_e32 v63, v56, v63
	v_div_scale_f32 v56, vcc, v49, v61, v49
	v_mul_f32_e32 v57, v56, v63
	v_fma_f32 v65, -v62, v57, v56
	v_fmac_f32_e32 v57, v65, v63
	v_fma_f32 v56, -v62, v57, v56
	v_div_scale_f32 v62, s[20:21], v60, v60, v48
	v_rcp_f32_e32 v65, v62
	v_div_fmas_f32 v56, v56, v63, v57
	v_div_fixup_f32 v49, v56, v61, v49
	v_div_scale_f32 v61, vcc, v48, v60, v48
	v_fma_f32 v56, -v62, v65, 1.0
	v_fmac_f32_e32 v65, v56, v65
	v_mul_f32_e32 v63, v61, v65
	v_fma_f32 v56, -v62, v63, v61
	v_fmac_f32_e32 v63, v56, v65
	v_mul_f32_e32 v56, 0xbfb8aa3b, v50
	v_mul_f32_e32 v57, 0xbfb8aa3b, v51
	v_exp_f32_e32 v56, v56
	v_exp_f32_e32 v57, v57
	v_fma_f32 v61, -v62, v63, v61
	v_div_fmas_f32 v61, v61, v65, v63
	v_div_fixup_f32 v48, v61, v60, v48
	v_pk_add_f32 v[56:57], v[56:57], 1.0 op_sel_hi:[1,0]
	v_pk_mul_f32 v[48:49], v[52:53], v[48:49]
	v_div_scale_f32 v62, s[20:21], v57, v57, v51
	v_rcp_f32_e32 v63, v62
	v_cvt_pk_bf16_f32 v48, v48, v49
	v_fma_f32 v49, -v62, v63, 1.0
	v_fmac_f32_e32 v63, v49, v63
	v_div_scale_f32 v49, vcc, v51, v57, v51
	v_mul_f32_e32 v52, v49, v63
	v_fma_f32 v53, -v62, v52, v49
	v_fmac_f32_e32 v52, v53, v63
	v_div_scale_f32 v53, s[20:21], v56, v56, v50
	v_rcp_f32_e32 v60, v53
	v_fma_f32 v49, -v62, v52, v49
	v_div_fmas_f32 v49, v49, v63, v52
	v_div_fixup_f32 v51, v49, v57, v51
	v_fma_f32 v49, -v53, v60, 1.0
	v_fmac_f32_e32 v60, v49, v60
	v_div_scale_f32 v49, vcc, v50, v56, v50
	v_mul_f32_e32 v52, v49, v60
	v_fma_f32 v57, -v53, v52, v49
	v_fmac_f32_e32 v52, v57, v60
	v_fma_f32 v49, -v53, v52, v49
	v_div_fmas_f32 v49, v49, v60, v52
	v_div_fixup_f32 v50, v49, v56, v50
	v_pk_mul_f32 v[50:51], v[54:55], v[50:51]
	s_nop 0
	v_cvt_pk_bf16_f32 v49, v50, v51
	global_store_dwordx2 v[58:59], v[48:49], off offset:32 sc0 sc1
	s_or_b64 exec, exec, s[18:19]
	v_cmp_lt_i32_e32 vcc, v166, v123
	s_and_saveexec_b64 s[18:19], vcc
	s_cbranch_execz .LBB0_1284
; __device__ __forceinline__ float siluf(float x) { return x / (1.f + __expf(-x)); }
; __device__ void phaseE1(const Params& p, char* smem) {
;     ...
;     auto epi = [&](f32x4 (&acc)[4][4], int mb, int nb) {
;       const int wn = nb >> 6, kg4 = nb & 63;
; #pragma unroll
;       for (int mi = 0; mi < 4; mi++) {
;         const int r = mb + mi * 16;
;         if (r < rows) {
; #pragma unroll
;           for (int ni = 0; ni < 2; ni++) {
;             f32x4 gv = acc[mi][ni], uv = acc[mi][ni + 2];
;             uint2 o;
;             o.x = pack2(siluf(gv[0]) * uv[0], siluf(gv[1]) * uv[1]);
;             o.y = pack2(siluf(gv[2]) * uv[2], siluf(gv[3]) * uv[3]);
;             *(uint2*)&p.H[(size_t)(slot0 + r) * DEXP + j0 + wn * 32 + ni * 16 + kg4] = o;
;           }
;         }
;       }
;     };
; __device__ __forceinline__ void xcd_barrier(const XcdBarrier& b) {
;   asm volatile("s_waitcnt vmcnt(0)" ::: "memory");
;   __syncthreads();
;   if (threadIdx.x == 0) {
;     unsigned* bar = b.bar;
;     __builtin_amdgcn_s_waitcnt(0);
;     unsigned nloc = b.st[0], nx = b.st[1];
;     if (nloc == 0u) { xcd_barrier_complete(bar, b.x, nloc, nx); b.st[0] = nloc; b.st[1] = nx; }
.LBB0_1289:
	v_mul_f32_e32 v48, 0xbfb8aa3b, v40
	v_mul_f32_e32 v49, 0xbfb8aa3b, v41
	v_exp_f32_e32 v48, v48
	v_exp_f32_e32 v49, v49
	s_nop 0
	v_pk_add_f32 v[48:49], v[48:49], 1.0 op_sel_hi:[1,0]
	s_nop 0
	v_div_scale_f32 v50, s[20:21], v49, v49, v41
	v_rcp_f32_e32 v51, v50
	v_div_scale_f32 v52, vcc, v41, v49, v41
	v_fma_f32 v53, -v50, v51, 1.0
	v_fmac_f32_e32 v51, v53, v51
	v_mul_f32_e32 v53, v52, v51
	v_fma_f32 v54, -v50, v53, v52
	v_fmac_f32_e32 v53, v54, v51
	v_fma_f32 v50, -v50, v53, v52
	v_div_scale_f32 v52, s[20:21], v48, v48, v40
	v_rcp_f32_e32 v54, v52
	v_div_fmas_f32 v50, v50, v51, v53
	v_div_fixup_f32 v41, v50, v49, v41
	v_mul_f32_e32 v51, 0xbfb8aa3b, v43
	v_fma_f32 v49, -v52, v54, 1.0
	v_fmac_f32_e32 v54, v49, v54
	v_div_scale_f32 v49, vcc, v40, v48, v40
	v_mul_f32_e32 v53, v49, v54
	v_fma_f32 v50, -v52, v53, v49
	v_fmac_f32_e32 v53, v50, v54
	v_mul_f32_e32 v50, 0xbfb8aa3b, v42
	v_exp_f32_e32 v50, v50
	v_exp_f32_e32 v51, v51
	v_fma_f32 v49, -v52, v53, v49
	v_div_fmas_f32 v49, v49, v54, v53
	v_div_fixup_f32 v40, v49, v48, v40
	v_pk_add_f32 v[50:51], v[50:51], 1.0 op_sel_hi:[1,0]
	v_pk_mul_f32 v[40:41], v[44:45], v[40:41]
	v_div_scale_f32 v52, s[20:21], v51, v51, v43
	v_rcp_f32_e32 v53, v52
	v_cvt_pk_bf16_f32 v40, v40, v41
	v_fma_f32 v41, -v52, v53, 1.0
	v_fmac_f32_e32 v53, v41, v53
	v_div_scale_f32 v41, vcc, v43, v51, v43
	v_mul_f32_e32 v44, v41, v53
	v_fma_f32 v45, -v52, v44, v41
	v_fmac_f32_e32 v44, v45, v53
	v_div_scale_f32 v45, s[20:21], v50, v50, v42
	v_rcp_f32_e32 v48, v45
	v_fma_f32 v41, -v52, v44, v41
	v_div_fmas_f32 v41, v41, v53, v44
	v_div_fixup_f32 v43, v41, v51, v43
	v_fma_f32 v41, -v45, v48, 1.0
	v_fmac_f32_e32 v48, v41, v48
	v_div_scale_f32 v41, vcc, v42, v50, v42
	v_mul_f32_e32 v44, v41, v48
	v_fma_f32 v49, -v45, v44, v41
	v_fmac_f32_e32 v44, v49, v48
	v_fma_f32 v41, -v45, v44, v41
	v_div_fmas_f32 v41, v41, v48, v44
	v_div_fixup_f32 v42, v41, v50, v42
	v_mul_f32_e32 v41, 0xbfb8aa3b, v32
	v_exp_f32_e32 v44, v41
	v_mul_f32_e32 v41, 0xbfb8aa3b, v33
	v_exp_f32_e32 v45, v41
	v_pk_mul_f32 v[42:43], v[46:47], v[42:43]
	v_pk_add_f32 v[44:45], v[44:45], 1.0 op_sel_hi:[1,0]
	s_nop 0
	v_div_scale_f32 v46, s[20:21], v45, v45, v33
	v_cvt_pk_bf16_f32 v41, v42, v43
	v_add_u32_e32 v42, v64, v166
	v_rcp_f32_e32 v47, v46
	v_ashrrev_i32_e32 v43, 31, v42
	v_lshlrev_b64 v[42:43], 10, v[42:43]
	v_lshl_add_u64 v[42:43], v[120:121], 0, v[42:43]
	global_store_dwordx2 v[42:43], v[40:41], off sc0 sc1
	v_fma_f32 v40, -v46, v47, 1.0
	v_fmac_f32_e32 v47, v40, v47
	v_div_scale_f32 v40, vcc, v33, v45, v33
	v_mul_f32_e32 v41, v40, v47
	v_fma_f32 v48, -v46, v41, v40
	v_fmac_f32_e32 v41, v48, v47
	v_fma_f32 v40, -v46, v41, v40
	v_div_scale_f32 v46, s[20:21], v44, v44, v32
	v_rcp_f32_e32 v48, v46
	v_div_fmas_f32 v40, v40, v47, v41
	v_div_fixup_f32 v33, v40, v45, v33
	v_div_scale_f32 v45, vcc, v32, v44, v32
	v_fma_f32 v40, -v46, v48, 1.0
	v_fmac_f32_e32 v48, v40, v48
	v_mul_f32_e32 v47, v45, v48
	v_fma_f32 v40, -v46, v47, v45
	v_fmac_f32_e32 v47, v40, v48
	v_mul_f32_e32 v40, 0xbfb8aa3b, v34
	v_mul_f32_e32 v41, 0xbfb8aa3b, v35
	v_exp_f32_e32 v40, v40
	v_exp_f32_e32 v41, v41
	v_fma_f32 v45, -v46, v47, v45
	v_div_fmas_f32 v45, v45, v48, v47
	v_div_fixup_f32 v32, v45, v44, v32
	v_pk_add_f32 v[40:41], v[40:41], 1.0 op_sel_hi:[1,0]
	v_pk_mul_f32 v[32:33], v[36:37], v[32:33]
	v_div_scale_f32 v46, s[20:21], v41, v41, v35
	v_rcp_f32_e32 v47, v46
	v_cvt_pk_bf16_f32 v32, v32, v33
	v_fma_f32 v33, -v46, v47, 1.0
	v_fmac_f32_e32 v47, v33, v47
	v_div_scale_f32 v33, vcc, v35, v41, v35
	v_mul_f32_e32 v36, v33, v47
	v_fma_f32 v37, -v46, v36, v33
	v_fmac_f32_e32 v36, v37, v47
	v_div_scale_f32 v37, s[20:21], v40, v40, v34
	v_rcp_f32_e32 v44, v37
	v_fma_f32 v33, -v46, v36, v33
	v_div_fmas_f32 v33, v33, v47, v36
	v_div_fixup_f32 v35, v33, v41, v35
	v_fma_f32 v33, -v37, v44, 1.0
	v_fmac_f32_e32 v44, v33, v44
	v_div_scale_f32 v33, vcc, v34, v40, v34
	v_mul_f32_e32 v36, v33, v44
	v_fma_f32 v41, -v37, v36, v33
	v_fmac_f32_e32 v36, v41, v44
	v_fma_f32 v33, -v37, v36, v33
	v_div_fmas_f32 v33, v33, v44, v36
	v_div_fixup_f32 v34, v33, v40, v34
	v_pk_mul_f32 v[34:35], v[38:39], v[34:35]
	s_nop 0
	v_cvt_pk_bf16_f32 v33, v34, v35
	global_store_dwordx2 v[42:43], v[32:33], off offset:32 sc0 sc1
	s_or_b64 exec, exec, s[18:19]
	v_cmp_lt_i32_e32 vcc, v167, v123
	s_and_saveexec_b64 s[18:19], vcc
	s_cbranch_execnz .LBB0_1285
	s_branch .LBB0_1286
.LBB0_1290:
	s_waitcnt vmcnt(0)
	s_barrier
	s_and_saveexec_b64 s[72:73], s[34:35]
	s_cbranch_execz .Le1_fin
	s_cmp_lt_i32 s51, 0
	s_cbranch_scc1 .Le1_fin
	s_lshr_b32 s49, s51, 5
	s_lshl_b32 s49, s49, 8
	s_and_b32 s50, s51, 31
	s_lshl_b32 s50, s50, 2
	s_add_u32 s49, s49, s50
	s_addk_i32 s49, 0x4604
	v_mov_b32_e32 v0, s49
	v_mov_b32_e32 v1, 1
	global_atomic_add v0, v1, s[82:83]
.Le1_fin:
	s_or_b64 exec, exec, s[72:73]
	s_waitcnt vmcnt(0)
	s_barrier
	s_and_saveexec_b64 s[0:1], s[34:35]
	s_cbranch_execz .LBB0_1342
	s_add_i32 s2, 0, 0x10300
	v_mov_b32_e32 v0, s2
	s_waitcnt vmcnt(0) expcnt(0) lgkmcnt(0)
	ds_read_b32 v2, v0
	s_add_i32 s2, 0, 0x10304
	v_mov_b32_e32 v0, s2
	ds_read_b32 v0, v0
	s_waitcnt lgkmcnt(1)
	v_cmp_ne_u32_e32 vcc, 0, v2
	s_cbranch_vccnz .LBB0_1306
	v_readlane_b32 s2, v240, 1
	v_readlane_b32 s3, v240, 2
	v_readlane_b32 s4, v240, 0
	s_mul_i32 s16, s3, s4
	s_mul_i32 s16, s16, s2
	s_add_u32 s2, s82, 0x1000
	s_addc_u32 s3, s83, 0
	s_add_u32 s4, s82, 0x1100
	s_addc_u32 s5, s83, 0
	s_add_u32 s6, s82, 0x1200
	s_addc_u32 s7, s83, 0
	s_add_u32 s8, s82, 0x1300
	s_addc_u32 s9, s83, 0
	s_mov_b32 s17, 1
	v_mov_b32_e32 v16, 0
	s_branch .LBB0_1294

; __device__ __forceinline__ unsigned xb_ld(unsigned* p)              { return __hip_atomic_load(p, __ATOMIC_RELAXED, __HIP_MEMORY_SCOPE_AGENT); }
; __device__ __forceinline__ unsigned xb_add(unsigned* p, unsigned v) { return __hip_atomic_fetch_add(p, v, __ATOMIC_RELAXED, __HIP_MEMORY_SCOPE_AGENT); }
; #define XB_SPIN(cond, bar) do { unsigned _sp = 0; while (cond) { __builtin_amdgcn_s_sleep(1); \
;     if ((++_sp & 255u) == 0u) { if (xb_ld(&(bar)[XB_TMO])) break; if (_sp > XB_SPIN_CAP) { atomicAdd(&(bar)[XB_TMO], 1u); break; } } } } while (0)
; __device__ __forceinline__ void xcd_barrier(const XcdBarrier& b) {
;     ...
;     unsigned nloc = b.st[0], nx = b.st[1];
;     if (nloc == 0u) { xcd_barrier_complete(bar, b.x, nloc, nx); b.st[0] = nloc; b.st[1] = nx; }
;     const unsigned old = xb_add(&bar[XB_XSUB(b.x)], 1u);
;     const unsigned gen = old / nloc;
;     if (old + 1u == (gen + 1u) * nloc) {
;       __builtin_amdgcn_fence(__ATOMIC_RELEASE, "agent");
;       asm volatile("s_waitcnt vmcnt(0)" ::: "memory");
;       const unsigned og = xb_add(&bar[XB_TOP], 1u);
;       const unsigned tg = og / nx;
;       if (og + 1u == (tg + 1u) * nx) xb_add(&bar[XB_TOPGEN], 1u);
;       else XB_SPIN(xb_ld(&bar[XB_TOPGEN]) == tg, bar);
;       __builtin_amdgcn_fence(__ATOMIC_ACQUIRE, "agent");
;       xb_add(&bar[XB_XGEN(b.x)], 1u);
;       asm volatile("s_waitcnt vmcnt(0)" ::: "memory");
;     } else {
;       XB_SPIN(xb_ld(&bar[XB_XGEN(b.x)]) == gen, bar);
;       __builtin_amdgcn_fence(__ATOMIC_ACQUIRE, "agent");
;       asm volatile("s_waitcnt vmcnt(0)" ::: "memory");
;     }
.LBB0_1306:
	s_branch .Lxb9_done
	s_waitcnt lgkmcnt(0)
	buffer_inv sc1
	s_waitcnt vmcnt(0)
	v_readfirstlane_b32 s2, v2
	v_readfirstlane_b32 s3, v0
	v_readlane_b32 s4, v240, 5
	s_lshl_b32 s4, s4, 8
	s_addk_i32 s4, 0x1400
	v_mov_b32_e32 v1, s4
	v_mov_b32_e32 v3, 1
	global_atomic_add v3, v1, v3, s[82:83] sc0
	s_mul_i32 s2, s2, 8
	s_mul_i32 s3, s3, 8
	v_readlane_b32 s4, v240, 42
	s_and_b32 s4, s4, 15
	s_lshl_b32 s4, s4, 8
	s_addk_i32 s4, 0x2400
	s_waitcnt vmcnt(0)
	v_readfirstlane_b32 s5, v3
	s_add_i32 s5, s5, 1
	s_cmp_lg_u32 s5, s2
	s_cbranch_scc1 .Lxb9_nm
	buffer_wbl2 sc1
	s_waitcnt vmcnt(0)
	s_mov_b64 exec, 0xffff
	v_mbcnt_lo_u32_b32 v1, -1, 0
	v_lshlrev_b32_e32 v1, 8, v1
	v_add_u32_e32 v1, 0x2400, v1
	v_mov_b32_e32 v3, 1
	global_atomic_add v1, v3, s[82:83]
	s_mov_b64 exec, 1
	s_branch .Lxb9_wait

; template <class F>
; __device__ __forceinline__ void xcd_queue_run(unsigned* qwords, int nper, char* smem_aux, F fn) {
;     ...
;       if (threadIdx.x == 0) *slot = (int)__hip_atomic_fetch_add(qwords + 64 * j, 1u, __ATOMIC_RELAXED, __HIP_MEMORY_SCOPE_AGENT);
;       __syncthreads();
;       const int q = *slot;
;       if (q >= nper) break;
; __device__ void phaseE2(const Params& p, char* smem) {
;     ...
;   xcd_queue_run(p.bar + QW_BASE + 1536, s_rb[NEXP], smem + 2 * GEMM_SMEM + 800, [&](int j, int q) {
;     const int rbg = q, nt = j;
;     int e = 0;
;     while (s_rb[e + 1] <= rbg) e++;
;     const int rb = rbg - s_rb[e];
;     const int cnt = p.cnt[e];
;     const int rows = min(128, cnt - rb * 128);
;     const int slot0 = s_off[e] + rb * 128;
;     const int n0 = nt * 128;
;     const float* wd = p.w_down + (size_t)e * DEXP * DM;
;     const float* lg = p.list_gate + e * CAP + rb * 128;
;     auto rowf = [&](int r) { int rr = r < rows ? r : 0; return (const void*)(p.H + (size_t)(slot0 + rr) * DEXP); };
.LBB0_1354:
	s_or_b64 exec, exec, s[18:19]
	s_mov_b64 s[18:19], src_shared_base
	s_waitcnt vmcnt(0)
	v_readfirstlane_b32 s2, v1
	s_cmp_lg_u32 s33, -1
	s_cselect_b32 s18, s19, 0
	v_add_u32_e32 v2, s2, v0
	s_cselect_b32 s2, s33, 0
	v_mov_b32_e32 v0, s2
	v_mov_b32_e32 v1, s18
	flat_store_dword v[0:1], v2 sc0 sc1
	s_waitcnt vmcnt(0)
	v_readfirstlane_b32 s49, v2
	v_readfirstlane_b32 s50, v108
	s_cmp_ge_i32 s49, s50
	s_cbranch_scc1 .Le2_nopoll
	s_lshr_b32 s50, s49, 5
	s_lshl_b32 s50, s50, 8
	s_and_b32 s49, s49, 31
	s_lshl_b32 s49, s49, 2
	s_add_u32 s49, s49, s50
	s_addk_i32 s49, 0x4604
	v_mov_b32_e32 v0, s49
	s_mov_b32 s50, 0
.Le2_poll:
	global_load_dword v1, v0, s[82:83] sc1
	s_waitcnt vmcnt(0)
	v_readfirstlane_b32 s49, v1
	s_cmp_ge_u32 s49, 8
	s_cbranch_scc1 .Le2_nopoll
	s_add_u32 s50, s50, 1
	s_sleep 1
	s_cmp_lt_u32 s50, 0x4000
	s_cbranch_scc1 .Le2_poll
.Le2_nopoll:
.LBB0_1355:
	s_or_b64 exec, exec, s[16:17]
	s_cmp_lg_u32 s33, -1
	s_cselect_b32 s2, s33, 0
	s_cselect_b32 s16, s1, 0
	v_mov_b32_e32 v0, s2
	v_mov_b32_e32 v1, s16
	s_waitcnt lgkmcnt(0)
	s_barrier
	flat_load_dword v2, v[0:1] sc0 sc1
	s_waitcnt vmcnt(0)
	s_mov_b64 s[18:19], -1
	s_waitcnt lgkmcnt(0)
	v_cmp_lt_i32_e32 vcc, v2, v108
	s_and_saveexec_b64 s[16:17], vcc
	s_cbranch_execz .LBB0_1350
	s_mov_b64 s[18:19], 0
	v_mbcnt_lo_u32_b32 v3, -1, 0
	v_mbcnt_hi_u32_b32 v3, -1, v3
	v_lshl_add_u32 v3, v3, 2, s24
	ds_read_b32 v3, v3
	s_waitcnt lgkmcnt(0)
	v_cmp_le_i32_e32 vcc, v3, v2
	s_bcnt1_i32_b64 s2, vcc
	v_mov_b32_e32 v80, s2
	s_lshl_b32 s20, s2, 21
	s_mov_b32 s21, 0
	v_lshl_add_u64 v[96:97], v[90:91], 0, s[20:21]
	s_or_b64 exec, exec, s[18:19]
	v_mul_u32_u24_e32 v0, 0x20100, v80
	v_mov_b32_e32 v1, 0
	v_lshl_add_u64 v[0:1], v[0:1], 0, s[62:63]
	global_load_dword v3, v[0:1], off
	v_lshl_add_u32 v4, v80, 2, 0
	v_lshlrev_b64 v[0:1], 21, v[80:81]
	v_add_u32_e32 v5, 0x10120, v4
	v_add_u32_e32 v4, 0x10000, v4
	v_lshl_add_u64 v[0:1], v[92:93], 0, v[0:1]
	ds_read_b32 v22, v5
	ds_read_b32 v23, v4
	v_add_co_u32_e32 v4, vcc, s26, v0
	v_mov_b32_e32 v64, 0
	s_nop 0
	v_addc_co_u32_e32 v5, vcc, 0, v1, vcc
	v_add_co_u32_e32 v6, vcc, s27, v0
	s_waitcnt lgkmcnt(1)
	v_sub_u32_e32 v2, v2, v22
	v_addc_co_u32_e32 v7, vcc, 0, v1, vcc
	v_add_co_u32_e32 v8, vcc, s28, v0
	v_lshlrev_b32_e32 v98, 7, v2
	s_nop 0
	v_addc_co_u32_e32 v9, vcc, 0, v1, vcc
	v_add_co_u32_e32 v10, vcc, s29, v0
	s_waitcnt lgkmcnt(0)
	v_add_u32_e32 v117, v23, v98
	v_addc_co_u32_e32 v11, vcc, 0, v1, vcc
	v_add_co_u32_e32 v12, vcc, s30, v0
	s_mov_b32 s2, 0
	s_nop 0
	v_addc_co_u32_e32 v13, vcc, 0, v1, vcc
	v_add_co_u32_e32 v14, vcc, s31, v0
	s_mov_b32 s47, 0
	s_nop 0
	v_addc_co_u32_e32 v15, vcc, 0, v1, vcc
	v_add_co_u32_e32 v16, vcc, s36, v0
	v_mov_b32_e32 v65, v64
	s_nop 0
	v_addc_co_u32_e32 v17, vcc, 0, v1, vcc
	v_add_co_u32_e32 v18, vcc, s25, v0
	global_load_dword v141, v[0:1], off
	global_load_dword v99, v[4:5], off offset:-4096
	global_load_dword v119, v[4:5], off
	global_load_dword v120, v[6:7], off offset:-4096
	global_load_dword v121, v[6:7], off
	global_load_dword v122, v[8:9], off offset:-4096
	global_load_dword v123, v[8:9], off
	global_load_dword v128, v[10:11], off offset:-4096
	global_load_dword v130, v[10:11], off
	global_load_dword v132, v[12:13], off offset:-4096
	global_load_dword v133, v[12:13], off
	global_load_dword v134, v[14:15], off offset:-4096
	global_load_dword v135, v[14:15], off
	global_load_dword v136, v[16:17], off offset:-4096
	global_load_dword v137, v[16:17], off
	v_addc_co_u32_e32 v19, vcc, 0, v1, vcc
	v_add_co_u32_e32 v20, vcc, s37, v0
	v_mov_b32_e32 v66, v64
	s_nop 0
	v_addc_co_u32_e32 v21, vcc, 0, v1, vcc
	v_mov_b32_e32 v67, v64
	v_mov_b32_e32 v76, v64
	v_mov_b32_e32 v77, v64
	v_mov_b32_e32 v78, v64
	v_mov_b32_e32 v79, v64
	v_mov_b32_e32 v72, v64
	v_mov_b32_e32 v73, v64
	v_mov_b32_e32 v74, v64
	v_mov_b32_e32 v75, v64
	v_mov_b32_e32 v68, v64
	v_mov_b32_e32 v69, v64
	v_mov_b32_e32 v70, v64
	v_mov_b32_e32 v71, v64
	v_mov_b32_e32 v60, v64
	v_mov_b32_e32 v61, v64
	v_mov_b32_e32 v62, v64
	v_mov_b32_e32 v63, v64
	v_mov_b32_e32 v56, v64
	v_mov_b32_e32 v57, v64
	v_mov_b32_e32 v58, v64
	v_mov_b32_e32 v59, v64
	v_mov_b32_e32 v52, v64
	v_mov_b32_e32 v53, v64
	v_mov_b32_e32 v54, v64
	v_mov_b32_e32 v55, v64
	v_mov_b32_e32 v48, v64
	v_mov_b32_e32 v49, v64
	v_mov_b32_e32 v50, v64
	s_waitcnt vmcnt(15)
; template <bool ABF, bool BBF, class RowF, class ColF, class Epi>
; __device__ __forceinline__ void gemm_tile(char* smem, int K, RowF rowptr, ColF colptr, int ldb, Epi epi) {
;     ...
;   auto gload = [&](int k0) {
; #pragma unroll
;     for (int i = 0; i < NA; i++) ra[i] = *(const u32x4*)(ap[i] + (size_t)k0 * (ABF ? 2 : 4));
;     if (BBF) {
; #pragma unroll
;       for (int i = 0; i < 4; i++) rbb[BBF ? i : 0] = *(const u32x4*)(bq[i] + (size_t)k0 * 2);
;     } else {
;       const float* b = bp + (size_t)k0 * ldb;
; #pragma unroll
;       for (int j = 0; j < 32; j++) rb[BBF ? 0 : j] = b[(size_t)j * ldb];
;     }
;   };
;   auto sstore = [&](int buf) {
;     u16* As = As0 + buf * (GEMM_SMEM / 2);
;     u16* Bs = As + BM * LDT;
; #pragma unroll
;     for (int i = 0; i < NA; i++) {
;       if (ABF) {
;         { const int row = ar0 + ARS * i; *(u32x4*)&As[row * LDT + (((ac >> 3) ^ ((row >> 1) & 7)) << 3)] = ra[i]; }
;       } else {
;         u32x2 v;
;         v[0] = pack2(__uint_as_float(ra[i][0]), __uint_as_float(ra[i][1]));
;         v[1] = pack2(__uint_as_float(ra[i][2]), __uint_as_float(ra[i][3]));
;         { const int row = ar0 + ARS * i; *(u32x2*)&As[row * LDT + (((ac >> 3) ^ ((row >> 1) & 7)) << 3) + (ac & 4)] = v; }
;       }
;     }
;     if (BBF) {
; #pragma unroll
;       for (int i = 0; i < 4; i++) { const int row = br0 + 32 * i; *(u32x4*)&Bs[row * LDT + (((bcc >> 3) ^ ((row >> 1) & 7)) << 3)] = rbb[BBF ? i : 0]; }
;     } else {
; #pragma unroll
;       for (int j = 0; j < 4; j++) {
;         u32x4 v;
;         v[0] = pack2(rb[BBF ? 0 : 8 * j + 0], rb[BBF ? 0 : 8 * j + 1]);
;         v[1] = pack2(rb[BBF ? 0 : 8 * j + 2], rb[BBF ? 0 : 8 * j + 3]);
;         v[2] = pack2(rb[BBF ? 0 : 8 * j + 4], rb[BBF ? 0 : 8 * j + 5]);
;         v[3] = pack2(rb[BBF ? 0 : 8 * j + 6], rb[BBF ? 0 : 8 * j + 7]);
;         *(u32x4*)&Bs[bc * LDT + (((kh * 4 + j) ^ ((bc >> 1) & 7)) << 3)] = v;
;       }
;     }
;   };
;   gload(0);
; __device__ void phaseE2(const Params& p, char* smem) {
;     ...
;     const int cnt = p.cnt[e];
;     const int rows = min(128, cnt - rb * 128);
;     const int slot0 = s_off[e] + rb * 128;
;     const int n0 = nt * 128;
;     const float* wd = p.w_down + (size_t)e * DEXP * DM;
;     const float* lg = p.list_gate + e * CAP + rb * 128;
;     auto rowf = [&](int r) { int rr = r < rows ? r : 0; return (const void*)(p.H + (size_t)(slot0 + rr) * DEXP); };
	v_sub_u32_e32 v2, v3, v98
	v_min_i32_e32 v118, 0x80, v2
	v_cmp_lt_i32_e32 vcc, v160, v118
	v_mov_b32_e32 v51, v64
	v_mov_b32_e32 v28, v64
	v_cndmask_b32_e32 v2, 0, v160, vcc
	v_cmp_lt_i32_e32 vcc, v150, v118
	v_add_u32_e32 v2, v2, v117
	v_mov_b32_e32 v29, v64
	v_cndmask_b32_e32 v3, 0, v150, vcc
	v_cmp_lt_i32_e32 vcc, v151, v118
	v_add_u32_e32 v4, v3, v117
	v_ashrrev_i32_e32 v3, 31, v2
	v_cndmask_b32_e32 v5, 0, v151, vcc
	v_cmp_lt_i32_e32 vcc, v152, v118
	v_add_u32_e32 v6, v5, v117
	v_ashrrev_i32_e32 v5, 31, v4
	v_cndmask_b32_e32 v7, 0, v152, vcc
	v_add_co_u32_e32 v10, vcc, s38, v0
	v_add_u32_e32 v8, v7, v117
	s_nop 0
	v_addc_co_u32_e32 v11, vcc, 0, v1, vcc
	v_add_co_u32_e32 v12, vcc, s39, v0
	v_ashrrev_i32_e32 v7, 31, v6
	s_nop 0
	v_addc_co_u32_e32 v13, vcc, 0, v1, vcc
	global_load_dword v138, v[18:19], off offset:-4096
	global_load_dword v139, v[18:19], off
	global_load_dword v140, v[20:21], off offset:-4096
	global_load_dword v142, v[20:21], off
	global_load_dword v143, v[10:11], off offset:-4096
	global_load_dword v144, v[10:11], off
	global_load_dword v145, v[12:13], off offset:-4096
	global_load_dword v146, v[12:13], off
	v_add_co_u32_e32 v10, vcc, s40, v0
	v_lshlrev_b64 v[16:17], 10, v[2:3]
	s_nop 0
	v_addc_co_u32_e32 v11, vcc, 0, v1, vcc
	v_add_co_u32_e32 v12, vcc, s41, v0
	v_ashrrev_i32_e32 v9, 31, v8
	s_nop 0
	v_addc_co_u32_e32 v13, vcc, 0, v1, vcc
	v_add_co_u32_e32 v14, vcc, s42, v0
	v_lshlrev_b64 v[22:23], 10, v[4:5]
	s_nop 0
	v_addc_co_u32_e32 v15, vcc, 0, v1, vcc
	v_add_co_u32_e32 v18, vcc, s43, v0
	v_lshlrev_b64 v[24:25], 10, v[6:7]
	s_nop 0
	v_addc_co_u32_e32 v19, vcc, 0, v1, vcc
	v_add_co_u32_e32 v0, vcc, s44, v0
	v_lshl_add_u64 v[2:3], v[86:87], 0, v[16:17]
	s_nop 0
	v_addc_co_u32_e32 v1, vcc, 0, v1, vcc
	global_load_dword v147, v[10:11], off offset:-4096
	global_load_dword v153, v[10:11], off
	global_load_dword v154, v[12:13], off offset:-4096
	global_load_dword v155, v[12:13], off
	global_load_dword v156, v[14:15], off offset:-4096
	global_load_dword v157, v[14:15], off
	global_load_dword v158, v[18:19], off offset:-4096
	global_load_dword v159, v[18:19], off
	global_load_dword v170, v[0:1], off
	v_lshlrev_b64 v[18:19], 10, v[8:9]
	v_lshl_add_u64 v[4:5], v[86:87], 0, v[22:23]
	v_lshl_add_u64 v[6:7], v[86:87], 0, v[24:25]
	v_lshl_add_u64 v[0:1], v[86:87], 0, v[18:19]
	v_lshrrev_b32_e32 v46, 2, v149
	v_lshrrev_b32_e32 v35, 4, v46
	v_xor_b32_e32 v35, v35, v46
	v_and_b32_e32 v35, 7, v35
	v_lshlrev_b32_e32 v34, 4, v35
	v_mov_b32_e32 v35, 0
	v_sub_u32_e32 v38, v34, v124
	v_lshrrev_b32_e32 v46, 6, v46
	v_ashrrev_i32_e32 v39, 31, v38
	v_readfirstlane_b32 s100, v46
	s_lshl_b32 s100, s100, 10
	v_readfirstlane_b32 s98, v118
	s_lshr_b32 s99, s100, 11
	s_cmp_le_u32 s98, 64
	s_cselect_b32 s98, 1, 0
	s_and_b32 s99, s99, s98
	s_add_u32 m0, s100, 0x0
	v_lshl_add_u64 v[42:43], v[2:3], 0, v[38:39]
	global_load_lds_dwordx4 v[42:43], off
	s_add_u32 m0, s100, 0x1000
	v_lshl_add_u64 v[42:43], v[4:5], 0, v[38:39]
	global_load_lds_dwordx4 v[42:43], off
	s_add_u32 m0, s100, 0x2000
	v_lshl_add_u64 v[42:43], v[6:7], 0, v[38:39]
	global_load_lds_dwordx4 v[42:43], off
	s_add_u32 m0, s100, 0x3000
	v_lshl_add_u64 v[42:43], v[0:1], 0, v[38:39]
	global_load_lds_dwordx4 v[42:43], off
	s_waitcnt vmcnt(34)
	v_cvt_pk_bf16_f32 v0, v141, v99
	s_waitcnt vmcnt(32)
	v_cvt_pk_bf16_f32 v1, v119, v120
	s_waitcnt vmcnt(30)
	v_cvt_pk_bf16_f32 v2, v121, v122
	s_waitcnt vmcnt(28)
	v_cvt_pk_bf16_f32 v3, v123, v128
	s_waitcnt vmcnt(26)
	v_cvt_pk_bf16_f32 v4, v130, v132
	s_waitcnt vmcnt(24)
	v_cvt_pk_bf16_f32 v5, v133, v134
	s_waitcnt vmcnt(22)
	v_cvt_pk_bf16_f32 v6, v135, v136
	v_lshl_add_u64 v[100:101], s[8:9], 0, v[16:17]
	v_lshl_add_u64 v[102:103], s[8:9], 0, v[22:23]
	v_lshl_add_u64 v[104:105], s[8:9], 0, v[24:25]
	v_lshl_add_u64 v[106:107], s[8:9], 0, v[18:19]
	v_mov_b32_e32 v30, v64
	v_mov_b32_e32 v31, v64
	v_mov_b32_e32 v24, v64
	v_mov_b32_e32 v25, v64
	v_mov_b32_e32 v26, v64
	v_mov_b32_e32 v27, v64
	v_mov_b32_e32 v20, v64
	v_mov_b32_e32 v21, v64
	v_mov_b32_e32 v22, v64
	v_mov_b32_e32 v23, v64
	v_mov_b32_e32 v16, v64
	v_mov_b32_e32 v17, v64
	v_mov_b32_e32 v18, v64
	v_mov_b32_e32 v19, v64
	s_waitcnt vmcnt(20)
	v_cvt_pk_bf16_f32 v7, v137, v138
	s_waitcnt vmcnt(18)
	v_cvt_pk_bf16_f32 v8, v139, v140
	s_waitcnt vmcnt(16)
	v_cvt_pk_bf16_f32 v9, v142, v143
	s_waitcnt vmcnt(14)
	v_cvt_pk_bf16_f32 v10, v144, v145
	s_waitcnt vmcnt(12)
	v_cvt_pk_bf16_f32 v11, v146, v147
	s_waitcnt vmcnt(10)
	v_cvt_pk_bf16_f32 v12, v153, v154
	s_waitcnt vmcnt(8)
	v_cvt_pk_bf16_f32 v13, v155, v156
	s_waitcnt vmcnt(6)
	v_cvt_pk_bf16_f32 v14, v157, v158
	s_waitcnt vmcnt(4)
	v_cvt_pk_bf16_f32 v15, v159, v170
	s_waitcnt vmcnt(3)
	s_waitcnt vmcnt(2)
	s_waitcnt vmcnt(1)
	s_waitcnt vmcnt(0)
	ds_write_b128 v113, v[0:3] offset:16384
	ds_write_b128 v114, v[4:7] offset:16384
	ds_write_b128 v115, v[8:11] offset:16384
	ds_write_b128 v116, v[12:15] offset:16384
	v_mov_b32_e32 v12, v64
	v_mov_b32_e32 v13, v64
	v_mov_b32_e32 v14, v64
	v_mov_b32_e32 v15, v64
	v_mov_b32_e32 v8, v64
	v_mov_b32_e32 v9, v64
	v_mov_b32_e32 v10, v64
	v_mov_b32_e32 v11, v64
	v_mov_b32_e32 v4, v64
	v_mov_b32_e32 v5, v64
	v_mov_b32_e32 v6, v64
	v_mov_b32_e32 v7, v64
	v_mov_b32_e32 v0, v64
	v_mov_b32_e32 v1, v64
	v_mov_b32_e32 v2, v64
	v_mov_b32_e32 v3, v64
	s_waitcnt lgkmcnt(0)
	s_barrier
	s_branch .LBB0_1360
